# NSA selected loop unrolled by two with double-buffered K/V staging registers: tile j+2 loads issued in iteration j
# baseline (speedup 1.0000x reference)
.LBB0_1646:
	s_and_saveexec_b64 s[0:1], vcc
	v_lshl_add_u32 v0, v6, 4, 0
	v_add_u32_e32 v0, 0x11200, v0
	ds_write_b128 v0, v[2:5]
	s_or_b64 exec, exec, s[0:1]
	s_mul_i32 s94, s20, 0x2c00000
	v_mov_b32_e32 v0, v1
	s_waitcnt lgkmcnt(0)
	s_barrier
	s_add_u32 s74, s18, s94
	s_getreg_b32 s0, hwreg(HW_REG_HW_ID, 0, 6)
	s_addc_u32 s75, s19, 0
	s_lshl_b32 s0, s0, 2
	s_and_b32 s0, s0, 0xfc
	v_add_u32_e32 v2, s0, v0
	v_add_u32_e32 v2, 0x24800, v2
	ds_read_b32 v2, v2
	s_cmp_lt_i32 s79, -3
	s_waitcnt lgkmcnt(0)
	v_readfirstlane_b32 s0, v2
	s_cbranch_scc1 .LBB0_1659
	v_mbcnt_lo_u32_b32 v0, -1, v0
	v_mbcnt_hi_u32_b32 v12, -1, v0
	v_lshl_add_u32 v0, s0, 6, v12
	s_add_i32 s1, 0, 0x11200
	v_ashrrev_i32_e32 v13, 3, v0
	v_mov_b64_e32 v[2:3], s[74:75]
	v_lshlrev_b32_e32 v0, 4, v12
	v_lshl_add_u32 v124, v98, 4, s1
	v_mad_i64_i32 v[2:3], s[0:1], v13, s89, v[2:3]
	v_and_b32_e32 v0, 0x70, v0
	v_lshl_add_u64 v[2:3], v[2:3], 0, v[0:1]
	global_load_dwordx4 v[6:9], v[2:3], off offset:3968
	s_nop 0
	global_load_dwordx4 v[2:5], v[2:3], off offset:3840
	v_bfe_u32 v14, v12, 2, 2
	v_lshrrev_b32_e32 v15, 3, v12
	v_and_b32_e32 v11, 31, v12
	v_and_or_b32 v14, v15, 4, v14
	v_bfe_u32 v10, v12, 5, 1
	v_mul_u32_u24_e32 v126, 0x90, v11
	v_and_b32_e32 v11, 16, v12
	v_mul_u32_u24_e32 v128, 0x90, v14
	v_lshlrev_b32_e32 v14, 2, v12
	v_lshlrev_b32_e32 v127, 4, v10
	v_lshlrev_b32_e32 v10, 2, v10
	v_and_or_b32 v11, v14, 12, v11
	v_lshlrev_b32_e32 v129, 1, v11
	v_or_b32_e32 v11, s21, v10
	v_cmp_gt_i32_e64 s[0:1], v10, v98
	v_cmp_lt_i32_e64 s[4:5], v10, v98
	v_or_b32_e32 v10, 33, v11
	v_cmp_gt_i32_e64 s[6:7], v10, v188
	v_or_b32_e32 v10, 2, v11
	v_cmp_gt_i32_e64 s[8:9], v10, v188
	v_or_b32_e32 v10, 34, v11
	v_cmp_gt_i32_e64 s[10:11], v10, v188
	v_or_b32_e32 v10, 3, v11
	v_cmp_gt_i32_e64 s[12:13], v10, v188
	v_or_b32_e32 v10, 35, v11
	v_cmp_gt_i32_e64 s[14:15], v10, v188
	v_or_b32_e32 v10, 8, v11
	v_cmp_gt_i32_e64 s[16:17], v10, v188
	v_or_b32_e32 v10, 40, v11
	v_cmp_gt_i32_e64 s[18:19], v10, v188
	v_or_b32_e32 v10, 9, v11
	v_cmp_gt_i32_e64 s[20:21], v10, v188
	v_or_b32_e32 v10, 41, v11
	v_mul_lo_u32 v125, v13, s23
	v_cmp_gt_i32_e64 s[22:23], v10, v188
	v_or_b32_e32 v10, 10, v11
	v_cmp_gt_i32_e64 s[24:25], v10, v188
	v_or_b32_e32 v10, 42, v11
	v_cmp_gt_i32_e64 s[26:27], v10, v188
	v_or_b32_e32 v10, 11, v11
	v_cmp_gt_i32_e64 s[28:29], v10, v188
	v_or_b32_e32 v10, 43, v11
	s_mov_b64 s[72:73], s[30:31]
	v_cmp_gt_i32_e64 s[30:31], v10, v188
	v_or_b32_e32 v10, 16, v11
	v_writelane_b32 v255, s36, 3
	v_cmp_gt_i32_e64 s[34:35], v10, v188
	v_or_b32_e32 v10, 48, v11
	v_writelane_b32 v255, s37, 4
	v_cmp_gt_i32_e64 s[36:37], v10, v188
	v_or_b32_e32 v10, 17, v11
	v_cmp_gt_i32_e64 s[38:39], v10, v188
	v_or_b32_e32 v10, 49, v11
	v_cmp_gt_i32_e64 s[40:41], v10, v188
	v_or_b32_e32 v10, 18, v11
	v_cmp_gt_i32_e64 s[42:43], v10, v188
	v_or_b32_e32 v10, 50, v11
	v_cmp_gt_i32_e64 s[44:45], v10, v188
	v_or_b32_e32 v10, 19, v11
	v_cmp_gt_i32_e64 s[46:47], v10, v188
	v_or_b32_e32 v10, 51, v11
	s_mov_b32 s83, s48
	v_cmp_gt_i32_e64 s[48:49], v10, v188
	v_or_b32_e32 v10, 24, v11
	v_cmp_gt_i32_e64 s[50:51], v10, v188
	v_or_b32_e32 v10, 56, v11
	v_cmp_gt_i32_e64 s[52:53], v10, v188
	v_or_b32_e32 v10, 25, v11
	v_cmp_gt_i32_e64 s[54:55], v10, v188
	v_or_b32_e32 v10, 57, v11
	v_cmp_gt_i32_e64 s[56:57], v10, v188
	v_or_b32_e32 v10, 26, v11
	v_cmp_gt_i32_e64 s[58:59], v10, v188
	v_or_b32_e32 v10, 58, v11
	v_cmp_gt_i32_e64 s[60:61], v10, v188
	v_or_b32_e32 v10, 27, v11
	v_cmp_gt_i32_e64 s[62:63], v10, v188
	v_or_b32_e32 v10, 59, v11
	v_or_b32_e32 v14, 32, v11
	v_cmp_gt_i32_e64 s[64:65], v10, v188
	v_mov_b64_e32 v[10:11], s[94:95]
	v_and_b32_e32 v12, 7, v12
	v_mad_i64_i32 v[10:11], s[80:81], v13, s89, v[10:11]
	v_lshlrev_b32_e32 v12, 4, v12
	v_mov_b32_e32 v13, v1
	v_lshl_add_u64 v[10:11], v[10:11], 0, v[12:13]
	v_mov_b32_e32 v62, v1
	v_mov_b32_e32 v63, v1
	v_lshl_add_u64 v[10:11], s[66:67], 0, v[10:11]
	s_mov_b64 s[66:67], 0xaa58f80
	v_mov_b32_e32 v48, v1
	v_mov_b32_e32 v49, v1
	v_mov_b32_e32 v50, v1
	v_mov_b32_e32 v51, v1
	v_mov_b32_e32 v52, v1
	v_mov_b32_e32 v53, v1
	v_mov_b32_e32 v54, v1
	v_mov_b32_e32 v55, v1
	v_mov_b32_e32 v56, v1
	v_mov_b32_e32 v57, v1
	v_mov_b32_e32 v58, v1
	v_mov_b32_e32 v59, v1
	v_mov_b32_e32 v60, v1
	v_mov_b32_e32 v61, v1
	v_mov_b64_e32 v[78:79], v[62:63]
	s_mov_b32 s82, 0x40c00000
	v_cmp_gt_i32_e64 s[2:3], v14, v188
	v_lshl_add_u64 v[14:15], v[10:11], 0, s[66:67]
	s_add_i32 s79, s79, 4
	s_mov_b32 s80, 0
	v_mov_b32_e32 v194, 0
	v_mov_b64_e32 v[76:77], v[60:61]
	v_mov_b64_e32 v[74:75], v[58:59]
	v_mov_b64_e32 v[72:73], v[56:57]
	v_mov_b64_e32 v[70:71], v[54:55]
	v_mov_b64_e32 v[68:69], v[52:53]
	v_mov_b64_e32 v[66:67], v[50:51]
	v_mov_b64_e32 v[64:65], v[48:49]
	v_mov_b32_e32 v130, 0
	s_cmp_lt_i32 s76, 1
	s_cbranch_scc1 .Lnsp_one
	global_load_dwordx4 v[208:211], v[14:15], off offset:-128
	global_load_dwordx4 v[212:215], v[14:15], off
.Lnsp_one:
	s_mov_b64 s[66:67], 0x58000
	v_lshl_add_u64 v[14:15], v[14:15], 0, s[66:67]
	s_branch .LBB0_1652

.LBB0_1651:
	s_add_i32 s80, s80, 1
	s_mov_b64 s[66:67], 0x58000
	s_cmp_lg_u32 s79, s80
	v_lshl_add_u64 v[14:15], v[14:15], 0, s[66:67]
	s_cbranch_scc0 .LBB0_1660
	s_branch .Lnsb_1652
.LBB0_1652:
	s_bitcmp1_b32 s80, 0
	s_cselect_b32 s66, 0x2400, 0
	s_add_i32 s81, s66, 0
	v_add3_u32 v10, s81, v125, v0
	s_cmp_ge_i32 s80, s76
	s_cbranch_scc1 .Lnsa_w0
	s_waitcnt vmcnt(2)
	s_branch .Lnsa_wd

.Lnsa_wd:
	ds_write_b128 v10, v[2:5]
	ds_write_b128 v10, v[6:9] offset:18432
	s_waitcnt lgkmcnt(0)
	s_barrier
	s_add_i32 s66, s80, 1
	s_cmp_ge_i32 s66, s76
	s_cbranch_scc1 .LBB0_1654
	global_load_dwordx4 v[2:5], v[14:15], off offset:-128
	global_load_dwordx4 v[6:9], v[14:15], off

.LBB0_1657:
	s_nop 7
	v_max_f32_e32 v132, v97, v97
	v_max_f32_e32 v133, v96, v96
	v_max_f32_e32 v132, v133, v132
	v_max3_f32 v133, v98, v99, v81
	v_max3_f32 v132, v132, v80, v82
	v_max3_f32 v132, v132, v83, v100
	v_max3_f32 v133, v133, v102, v103
	v_max3_f32 v132, v132, v101, v84
	v_max3_f32 v133, v133, v86, v87
	v_max3_f32 v132, v132, v85, v104
	v_max3_f32 v133, v133, v106, v107
	v_max3_f32 v132, v132, v105, v88
	v_max3_f32 v133, v133, v90, v91
	v_max3_f32 v132, v132, v89, v108
	v_max3_f32 v133, v133, v110, v111
	v_add_u32_e32 v10, s81, v128
	v_max3_f32 v132, v132, v109, v92
	v_max3_f32 v133, v133, v94, v95
	v_add_u32_e32 v131, v10, v129
	v_max3_f32 v132, v132, v93, v133
	v_mov_b32_e32 v133, v1
	ds_read_b64_tr_b16 v[120:121], v131 offset:18432
	ds_read_b64_tr_b16 v[122:123], v131 offset:19584
	ds_read_b64_tr_b16 v[118:119], v131 offset:19648
	ds_read_b64_tr_b16 v[116:117], v131 offset:18496
	ds_read_b64_tr_b16 v[112:113], v131 offset:20736
	ds_read_b64_tr_b16 v[114:115], v131 offset:21888
	ds_read_b64_tr_b16 v[12:13], v131 offset:21952
	ds_read_b64_tr_b16 v[10:11], v131 offset:20800
	s_nop 0
	v_mbcnt_lo_u32_b32 v133, -1, v133
	v_mbcnt_hi_u32_b32 v133, -1, v133
	v_lshlrev_b32_e32 v133, 2, v133
	v_xor_b32_e32 v133, 0x80, v133
	ds_bpermute_b32 v133, v133, v132
	s_waitcnt lgkmcnt(0)
	v_max_f32_e32 v133, v133, v133
	v_max_f32_e32 v132, v132, v133
	v_cmp_lt_f32_e32 vcc, s82, v132
	s_cbranch_vccz .LBB0_1650
	v_max_f32_e32 v132, v132, v132
	v_max_f32_e32 v133, 0, v132
	v_exp_f32_e64 v132, -v133
	v_add_f32_e32 v130, v130, v133
	v_sub_f32_e32 v111, v111, v133
	v_sub_f32_e32 v110, v110, v133
	v_mul_f32_e32 v194, v194, v132
	v_sub_f32_e32 v109, v109, v133
	v_sub_f32_e32 v108, v108, v133
	v_sub_f32_e32 v107, v107, v133
	v_sub_f32_e32 v106, v106, v133
	v_sub_f32_e32 v105, v105, v133
	v_sub_f32_e32 v104, v104, v133
	v_sub_f32_e32 v103, v103, v133
	v_sub_f32_e32 v102, v102, v133
	v_sub_f32_e32 v101, v101, v133
	v_sub_f32_e32 v100, v100, v133
	v_sub_f32_e32 v99, v99, v133
	v_sub_f32_e32 v98, v98, v133
	v_sub_f32_e32 v97, v97, v133
	v_sub_f32_e32 v96, v96, v133
	v_sub_f32_e32 v95, v95, v133
	v_sub_f32_e32 v94, v94, v133
	v_sub_f32_e32 v93, v93, v133
	v_sub_f32_e32 v92, v92, v133
	v_sub_f32_e32 v91, v91, v133
	v_sub_f32_e32 v90, v90, v133
	v_sub_f32_e32 v89, v89, v133
	v_sub_f32_e32 v88, v88, v133
	v_sub_f32_e32 v87, v87, v133
	v_sub_f32_e32 v86, v86, v133
	v_sub_f32_e32 v85, v85, v133
	v_sub_f32_e32 v84, v84, v133
	v_sub_f32_e32 v83, v83, v133
	v_sub_f32_e32 v82, v82, v133
	v_sub_f32_e32 v81, v81, v133
	v_sub_f32_e32 v80, v80, v133
	v_pk_mul_f32 v[78:79], v[78:79], v[132:133] op_sel_hi:[1,0]
	v_pk_mul_f32 v[76:77], v[76:77], v[132:133] op_sel_hi:[1,0]
	v_pk_mul_f32 v[74:75], v[74:75], v[132:133] op_sel_hi:[1,0]
	v_pk_mul_f32 v[72:73], v[72:73], v[132:133] op_sel_hi:[1,0]
	v_pk_mul_f32 v[70:71], v[70:71], v[132:133] op_sel_hi:[1,0]
	v_pk_mul_f32 v[68:69], v[68:69], v[132:133] op_sel_hi:[1,0]
	v_pk_mul_f32 v[66:67], v[66:67], v[132:133] op_sel_hi:[1,0]
	v_pk_mul_f32 v[64:65], v[64:65], v[132:133] op_sel_hi:[1,0]
	v_pk_mul_f32 v[62:63], v[62:63], v[132:133] op_sel_hi:[1,0]
	v_pk_mul_f32 v[60:61], v[60:61], v[132:133] op_sel_hi:[1,0]
	v_pk_mul_f32 v[58:59], v[58:59], v[132:133] op_sel_hi:[1,0]
	v_pk_mul_f32 v[56:57], v[56:57], v[132:133] op_sel_hi:[1,0]
	v_pk_mul_f32 v[54:55], v[54:55], v[132:133] op_sel_hi:[1,0]
	v_pk_mul_f32 v[52:53], v[52:53], v[132:133] op_sel_hi:[1,0]
	v_pk_mul_f32 v[50:51], v[50:51], v[132:133] op_sel_hi:[1,0]
	v_pk_mul_f32 v[48:49], v[48:49], v[132:133] op_sel_hi:[1,0]
	s_branch .LBB0_1650
.Lnsb_1650:
	v_exp_f32_e32 v96, v96
	v_exp_f32_e32 v97, v97
	v_exp_f32_e32 v98, v98
	v_exp_f32_e32 v99, v99
	v_exp_f32_e32 v100, v100
	v_exp_f32_e32 v136, v84
	v_exp_f32_e32 v101, v101
	v_exp_f32_e32 v137, v85
	v_exp_f32_e32 v84, v102
	v_exp_f32_e32 v85, v103
	v_exp_f32_e32 v132, v80
	v_exp_f32_e32 v133, v81
	v_exp_f32_e32 v134, v82
	v_exp_f32_e32 v135, v83
	v_cvt_pk_bf16_f32 v80, v96, v97
	v_cvt_pk_bf16_f32 v81, v98, v99
	v_cvt_pk_bf16_f32 v82, v100, v101
	v_cvt_pk_bf16_f32 v83, v84, v85
	v_exp_f32_e32 v102, v86
	v_exp_f32_e32 v103, v87
	v_mfma_f32_32x32x16_bf16 v[64:79], v[120:123], v[80:83], v[64:79]
	v_exp_f32_e32 v86, v104
	v_exp_f32_e32 v87, v105
	v_exp_f32_e32 v104, v106
	v_exp_f32_e32 v105, v107
	v_exp_f32_e32 v106, v108
	v_exp_f32_e32 v107, v109
	v_exp_f32_e32 v108, v110
	v_mfma_f32_32x32x16_bf16 v[48:63], v[116:119], v[80:83], v[48:63]
	v_exp_f32_e32 v109, v111
	v_exp_f32_e32 v90, v90
	v_exp_f32_e32 v91, v91
	v_exp_f32_e32 v88, v88
	v_exp_f32_e32 v89, v89
	v_cvt_pk_bf16_f32 v80, v86, v87
	v_cvt_pk_bf16_f32 v81, v104, v105
	v_cvt_pk_bf16_f32 v82, v106, v107
	v_cvt_pk_bf16_f32 v83, v108, v109
	v_pk_add_f32 v[110:111], v[102:103], v[84:85]
	v_pk_add_f32 v[84:85], v[134:135], v[98:99]
	v_mfma_f32_32x32x16_bf16 v[64:79], v[112:115], v[80:83], v[64:79]
	v_add_f32_e64 v98, v90, v104
	v_add_f32_e64 v99, v91, v105
	v_add_f32_e64 v138, v88, v86
	v_add_f32_e64 v139, v89, v87
	v_mov_b32_e32 v86, v84
	v_mov_b32_e32 v87, v98
	v_mov_b32_e32 v98, v85
	v_pk_add_f32 v[98:99], v[86:87], v[98:99]
	ds_read_b64_tr_b16 v[84:85], v131 offset:23040
	ds_read_b64_tr_b16 v[86:87], v131 offset:24192
	v_mfma_f32_32x32x16_bf16 v[48:63], v[10:13], v[80:83], v[48:63]
	ds_read_b64_tr_b16 v[82:83], v131 offset:24256
	ds_read_b64_tr_b16 v[80:81], v131 offset:23104
	v_exp_f32_e32 v92, v92
	v_exp_f32_e32 v93, v93
	v_cvt_pk_bf16_f32 v10, v132, v133
	v_cvt_pk_bf16_f32 v11, v134, v135
	v_cvt_pk_bf16_f32 v12, v136, v137
	v_cvt_pk_bf16_f32 v13, v102, v103
	v_pk_add_f32 v[96:97], v[132:133], v[96:97]
	v_pk_add_f32 v[100:101], v[136:137], v[100:101]
	s_waitcnt lgkmcnt(2)
	v_mfma_f32_32x32x16_bf16 v[64:79], v[84:87], v[10:13], v[64:79]
	v_add_f32_e64 v122, v92, v106
	v_add_f32_e64 v123, v93, v107
	v_mov_b32_e32 v116, v96
	v_mov_b32_e32 v117, v138
	v_mov_b32_e32 v138, v97
	v_pk_add_f32 v[96:97], v[116:117], v[138:139]
	v_mov_b32_e32 v84, v100
	v_mov_b32_e32 v85, v122
	s_waitcnt lgkmcnt(0)
	v_mfma_f32_32x32x16_bf16 v[48:63], v[80:83], v[10:13], v[48:63]
	v_mov_b32_e32 v122, v101
	v_exp_f32_e32 v94, v94
	v_exp_f32_e32 v95, v95
	v_pk_add_f32 v[96:97], v[96:97], v[98:99]
	v_pk_add_f32 v[98:99], v[84:85], v[122:123]
	ds_read_b64_tr_b16 v[84:85], v131 offset:25344
	ds_read_b64_tr_b16 v[86:87], v131 offset:26496
	ds_read_b64_tr_b16 v[82:83], v131 offset:26560
	ds_read_b64_tr_b16 v[80:81], v131 offset:25408
	v_cvt_pk_bf16_f32 v10, v88, v89
	v_cvt_pk_bf16_f32 v11, v90, v91
	v_cvt_pk_bf16_f32 v12, v92, v93
	v_cvt_pk_bf16_f32 v13, v94, v95
	v_pk_add_f32 v[120:121], v[94:95], v[108:109]
	v_mov_b32_e32 v100, v110
	s_waitcnt lgkmcnt(2)
	v_mfma_f32_32x32x16_bf16 v[64:79], v[84:87], v[10:13], v[64:79]
	v_mov_b32_e32 v101, v120
	v_mov_b32_e32 v120, v111
	v_add_f32_e64 v84, v100, v120
	v_add_f32_e64 v85, v101, v121
	v_add_f32_e64 v84, v98, v84
	v_add_f32_e64 v85, v99, v85
	s_waitcnt lgkmcnt(0)
	v_mfma_f32_32x32x16_bf16 v[48:63], v[80:83], v[10:13], v[48:63]
	v_add_f32_e64 v84, v96, v84
	v_add_f32_e64 v85, v97, v85
	v_add_f32_e32 v84, v84, v85
	v_add_f32_e32 v194, v194, v84

.Lnsb_wd:
	ds_write_b128 v10, v[208:211]
	ds_write_b128 v10, v[212:215] offset:18432
	s_waitcnt lgkmcnt(0)
	s_barrier
	s_add_i32 s66, s80, 1
	s_cmp_ge_i32 s66, s76
	s_cbranch_scc1 .Lnsb_1654
	global_load_dwordx4 v[208:211], v[14:15], off offset:-128
	global_load_dwordx4 v[212:215], v[14:15], off
